# GEMM K loops: static s_setprio 1 for waves 0-3 instead (flips deleted)
# speedup vs baseline: 1.0079x; 1.0032x over previous
.LBB0_214:
	s_ashr_i32 s19, s18, 31
	s_lshl_b64 s[20:21], s[18:19], 19
	s_add_u32 s20, s62, s20
	s_addc_u32 s21, s63, s21
	s_and_b64 s[34:35], s[2:3], exec
	s_cselect_b32 s19, s21, s55
	s_cselect_b32 s86, s20, s54
	s_ashr_i32 s15, s14, 31
	s_lshl_b64 s[34:35], s[14:15], 19
	s_add_u32 s34, s26, s34
	s_addc_u32 s35, s27, s35
	s_and_b64 s[60:61], s[2:3], exec
	s_cselect_b32 s15, s35, s59
	s_cselect_b32 s87, s34, s58
	s_add_u32 s54, s54, 0x40080
	s_addc_u32 s55, s55, 0
	s_add_u32 s88, s58, 0x100
	s_addc_u32 s89, s59, 0
	s_mov_b32 s90, -2
	v_mov_b64_e32 v[0:1], 0
	v_mov_b64_e32 v[2:3], 0
	v_mov_b64_e32 v[4:5], 0
	v_mov_b64_e32 v[6:7], 0
	v_mov_b64_e32 v[8:9], 0
	v_mov_b64_e32 v[10:11], 0
	v_mov_b64_e32 v[12:13], 0
	v_mov_b64_e32 v[14:15], 0
	v_mov_b64_e32 v[16:17], 0
	v_mov_b64_e32 v[18:19], 0
	v_mov_b64_e32 v[20:21], 0
	v_mov_b64_e32 v[22:23], 0
	v_mov_b64_e32 v[24:25], 0
	v_mov_b64_e32 v[26:27], 0
	v_mov_b64_e32 v[28:29], 0
	v_mov_b64_e32 v[30:31], 0
	v_mov_b64_e32 v[32:33], 0
	v_mov_b64_e32 v[34:35], 0
	v_mov_b64_e32 v[36:37], 0
	v_mov_b64_e32 v[38:39], 0
	v_mov_b64_e32 v[40:41], 0
	v_mov_b64_e32 v[42:43], 0
	v_mov_b64_e32 v[44:45], 0
	v_mov_b64_e32 v[46:47], 0
	v_mov_b64_e32 v[48:49], 0
	v_mov_b64_e32 v[50:51], 0
	v_mov_b64_e32 v[52:53], 0
	v_mov_b64_e32 v[54:55], 0
	v_mov_b64_e32 v[56:57], 0
	v_mov_b64_e32 v[58:59], 0
	v_mov_b64_e32 v[60:61], 0
	v_mov_b64_e32 v[62:63], 0
	v_mov_b64_e32 v[64:65], 0
	v_mov_b64_e32 v[66:67], 0
	v_mov_b64_e32 v[68:69], 0
	v_mov_b64_e32 v[70:71], 0
	v_mov_b64_e32 v[72:73], 0
	v_mov_b64_e32 v[74:75], 0
	v_mov_b64_e32 v[76:77], 0
	v_mov_b64_e32 v[78:79], 0
	v_mov_b64_e32 v[80:81], 0
	v_mov_b64_e32 v[82:83], 0
	v_mov_b64_e32 v[84:85], 0
	v_mov_b64_e32 v[86:87], 0
	v_mov_b64_e32 v[88:89], 0
	v_mov_b64_e32 v[90:91], 0
	v_mov_b64_e32 v[92:93], 0
	v_mov_b64_e32 v[94:95], 0
	v_mov_b64_e32 v[96:97], 0
	v_mov_b64_e32 v[98:99], 0
	v_mov_b64_e32 v[100:101], 0
	v_mov_b64_e32 v[102:103], 0
	v_mov_b64_e32 v[104:105], 0
	v_mov_b64_e32 v[106:107], 0
	v_mov_b64_e32 v[108:109], 0
	v_mov_b64_e32 v[110:111], 0
	v_mov_b64_e32 v[112:113], 0
	v_mov_b64_e32 v[114:115], 0
	v_mov_b64_e32 v[116:117], 0
	v_mov_b64_e32 v[118:119], 0
	v_mov_b64_e32 v[120:121], 0
	v_mov_b64_e32 v[122:123], 0
	v_mov_b64_e32 v[124:125], 0
	v_mov_b64_e32 v[126:127], 0
	v_lshrrev_b32_e32 v253, 8, v200
	s_nop 0
	v_readfirstlane_b32 s98, v253
	s_cmp_lg_u32 s98, 0
	s_cbranch_scc1 .Lgp_215
	s_setprio 1

.LBB0_383:
	s_ashr_i32 s45, s44, 31
	s_lshl_b64 s[50:51], s[44:45], 19
	s_add_u32 s50, s67, s50
	s_addc_u32 s51, s68, s51
	s_and_b64 s[54:55], s[2:3], exec
	s_cselect_b32 s17, s51, s59
	s_cselect_b32 s45, s50, s58
	s_ashr_i32 s35, s34, 31
	s_lshl_b64 s[54:55], s[34:35], 19
	s_add_u32 s54, s69, s54
	s_addc_u32 s55, s72, s55
	s_and_b64 s[62:63], s[2:3], exec
	s_cselect_b32 s35, s55, s61
	s_cselect_b32 s89, s54, s60
	s_add_u32 s58, s58, 0x40080
	s_addc_u32 s59, s59, 0
	s_add_u32 s90, s60, 0x100
	s_addc_u32 s91, s61, 0
	s_mov_b32 s92, -2
	v_mov_b64_e32 v[0:1], 0
	v_mov_b64_e32 v[2:3], 0
	v_mov_b64_e32 v[4:5], 0
	v_mov_b64_e32 v[6:7], 0
	v_mov_b64_e32 v[8:9], 0
	v_mov_b64_e32 v[10:11], 0
	v_mov_b64_e32 v[12:13], 0
	v_mov_b64_e32 v[14:15], 0
	v_mov_b64_e32 v[16:17], 0
	v_mov_b64_e32 v[18:19], 0
	v_mov_b64_e32 v[20:21], 0
	v_mov_b64_e32 v[22:23], 0
	v_mov_b64_e32 v[24:25], 0
	v_mov_b64_e32 v[26:27], 0
	v_mov_b64_e32 v[28:29], 0
	v_mov_b64_e32 v[30:31], 0
	v_mov_b64_e32 v[32:33], 0
	v_mov_b64_e32 v[34:35], 0
	v_mov_b64_e32 v[36:37], 0
	v_mov_b64_e32 v[38:39], 0
	v_mov_b64_e32 v[40:41], 0
	v_mov_b64_e32 v[42:43], 0
	v_mov_b64_e32 v[44:45], 0
	v_mov_b64_e32 v[46:47], 0
	v_mov_b64_e32 v[48:49], 0
	v_mov_b64_e32 v[50:51], 0
	v_mov_b64_e32 v[52:53], 0
	v_mov_b64_e32 v[54:55], 0
	v_mov_b64_e32 v[56:57], 0
	v_mov_b64_e32 v[58:59], 0
	v_mov_b64_e32 v[60:61], 0
	v_mov_b64_e32 v[62:63], 0
	v_mov_b64_e32 v[64:65], 0
	v_mov_b64_e32 v[66:67], 0
	v_mov_b64_e32 v[68:69], 0
	v_mov_b64_e32 v[70:71], 0
	v_mov_b64_e32 v[72:73], 0
	v_mov_b64_e32 v[74:75], 0
	v_mov_b64_e32 v[76:77], 0
	v_mov_b64_e32 v[78:79], 0
	v_mov_b64_e32 v[80:81], 0
	v_mov_b64_e32 v[82:83], 0
	v_mov_b64_e32 v[84:85], 0
	v_mov_b64_e32 v[86:87], 0
	v_mov_b64_e32 v[88:89], 0
	v_mov_b64_e32 v[90:91], 0
	v_mov_b64_e32 v[92:93], 0
	v_mov_b64_e32 v[94:95], 0
	v_mov_b64_e32 v[96:97], 0
	v_mov_b64_e32 v[98:99], 0
	v_mov_b64_e32 v[100:101], 0
	v_mov_b64_e32 v[102:103], 0
	v_mov_b64_e32 v[104:105], 0
	v_mov_b64_e32 v[106:107], 0
	v_mov_b64_e32 v[108:109], 0
	v_mov_b64_e32 v[110:111], 0
	v_mov_b64_e32 v[112:113], 0
	v_mov_b64_e32 v[114:115], 0
	v_mov_b64_e32 v[116:117], 0
	v_mov_b64_e32 v[118:119], 0
	v_mov_b64_e32 v[120:121], 0
	v_mov_b64_e32 v[122:123], 0
	v_mov_b64_e32 v[124:125], 0
	v_mov_b64_e32 v[126:127], 0
	v_lshrrev_b32_e32 v253, 8, v200
	s_nop 0
	v_readfirstlane_b32 s98, v253
	s_cmp_lg_u32 s98, 0
	s_cbranch_scc1 .Lgp_384
	s_setprio 1

.LBB0_728:
	s_ashr_i32 s45, s44, 31
	s_lshl_b64 s[50:51], s[44:45], 19
	s_add_u32 s50, s11, s50
	s_addc_u32 s51, s17, s51
	s_and_b64 s[54:55], s[2:3], exec
	s_cselect_b32 s45, s51, s59
	s_cselect_b32 s78, s50, s58
	s_ashr_i32 s35, s34, 31
	s_lshl_b64 s[54:55], s[34:35], 19
	s_add_u32 s54, s64, s54
	s_addc_u32 s55, s65, s55
	s_and_b64 s[62:63], s[2:3], exec
	s_cselect_b32 s35, s55, s61
	s_cselect_b32 s79, s54, s60
	s_add_u32 s58, s58, 0x40080
	s_addc_u32 s59, s59, 0
	s_add_u32 s80, s60, 0x100
	s_addc_u32 s81, s61, 0
	s_mov_b32 s82, -2
	v_mov_b64_e32 v[0:1], 0
	v_mov_b64_e32 v[2:3], 0
	v_mov_b64_e32 v[4:5], 0
	v_mov_b64_e32 v[6:7], 0
	v_mov_b64_e32 v[8:9], 0
	v_mov_b64_e32 v[10:11], 0
	v_mov_b64_e32 v[12:13], 0
	v_mov_b64_e32 v[14:15], 0
	v_mov_b64_e32 v[16:17], 0
	v_mov_b64_e32 v[18:19], 0
	v_mov_b64_e32 v[20:21], 0
	v_mov_b64_e32 v[22:23], 0
	v_mov_b64_e32 v[24:25], 0
	v_mov_b64_e32 v[26:27], 0
	v_mov_b64_e32 v[28:29], 0
	v_mov_b64_e32 v[30:31], 0
	v_mov_b64_e32 v[32:33], 0
	v_mov_b64_e32 v[34:35], 0
	v_mov_b64_e32 v[36:37], 0
	v_mov_b64_e32 v[38:39], 0
	v_mov_b64_e32 v[40:41], 0
	v_mov_b64_e32 v[42:43], 0
	v_mov_b64_e32 v[44:45], 0
	v_mov_b64_e32 v[46:47], 0
	v_mov_b64_e32 v[48:49], 0
	v_mov_b64_e32 v[50:51], 0
	v_mov_b64_e32 v[52:53], 0
	v_mov_b64_e32 v[54:55], 0
	v_mov_b64_e32 v[56:57], 0
	v_mov_b64_e32 v[58:59], 0
	v_mov_b64_e32 v[60:61], 0
	v_mov_b64_e32 v[62:63], 0
	v_mov_b64_e32 v[64:65], 0
	v_mov_b64_e32 v[66:67], 0
	v_mov_b64_e32 v[68:69], 0
	v_mov_b64_e32 v[70:71], 0
	v_mov_b64_e32 v[72:73], 0
	v_mov_b64_e32 v[74:75], 0
	v_mov_b64_e32 v[76:77], 0
	v_mov_b64_e32 v[78:79], 0
	v_mov_b64_e32 v[80:81], 0
	v_mov_b64_e32 v[82:83], 0
	v_mov_b64_e32 v[84:85], 0
	v_mov_b64_e32 v[86:87], 0
	v_mov_b64_e32 v[88:89], 0
	v_mov_b64_e32 v[90:91], 0
	v_mov_b64_e32 v[92:93], 0
	v_mov_b64_e32 v[94:95], 0
	v_mov_b64_e32 v[96:97], 0
	v_mov_b64_e32 v[98:99], 0
	v_mov_b64_e32 v[100:101], 0
	v_mov_b64_e32 v[102:103], 0
	v_mov_b64_e32 v[104:105], 0
	v_mov_b64_e32 v[106:107], 0
	v_mov_b64_e32 v[108:109], 0
	v_mov_b64_e32 v[110:111], 0
	v_mov_b64_e32 v[112:113], 0
	v_mov_b64_e32 v[114:115], 0
	v_mov_b64_e32 v[116:117], 0
	v_mov_b64_e32 v[118:119], 0
	v_mov_b64_e32 v[120:121], 0
	v_mov_b64_e32 v[122:123], 0
	v_mov_b64_e32 v[124:125], 0
	v_mov_b64_e32 v[126:127], 0
	v_lshrrev_b32_e32 v253, 8, v200
	s_nop 0
	v_readfirstlane_b32 s98, v253
	s_cmp_lg_u32 s98, 0
	s_cbranch_scc1 .Lgp_729
	s_setprio 1

.LBB0_865:
	s_ashr_i32 s55, s54, 31
	s_lshl_b64 s[58:59], s[54:55], 19
	s_add_u32 s58, s17, s58
	s_addc_u32 s59, s68, s59
	s_and_b64 s[60:61], s[6:7], exec
	s_cselect_b32 s55, s59, s63
	s_cselect_b32 s86, s58, s62
	s_ashr_i32 s53, s52, 31
	s_lshl_b64 s[60:61], s[52:53], 19
	s_add_u32 s60, s69, s60
	s_addc_u32 s61, s70, s61
	s_and_b64 s[66:67], s[6:7], exec
	s_cselect_b32 s53, s61, s65
	s_cselect_b32 s87, s60, s64
	s_add_u32 s62, s62, 0x40080
	s_addc_u32 s63, s63, 0
	s_add_u32 s88, s64, 0x100
	s_addc_u32 s89, s65, 0
	s_mov_b32 s90, -2
	v_mov_b64_e32 v[0:1], 0
	v_mov_b64_e32 v[2:3], 0
	v_mov_b64_e32 v[4:5], 0
	v_mov_b64_e32 v[6:7], 0
	v_mov_b64_e32 v[8:9], 0
	v_mov_b64_e32 v[10:11], 0
	v_mov_b64_e32 v[12:13], 0
	v_mov_b64_e32 v[14:15], 0
	v_mov_b64_e32 v[16:17], 0
	v_mov_b64_e32 v[18:19], 0
	v_mov_b64_e32 v[20:21], 0
	v_mov_b64_e32 v[22:23], 0
	v_mov_b64_e32 v[24:25], 0
	v_mov_b64_e32 v[26:27], 0
	v_mov_b64_e32 v[28:29], 0
	v_mov_b64_e32 v[30:31], 0
	v_mov_b64_e32 v[32:33], 0
	v_mov_b64_e32 v[34:35], 0
	v_mov_b64_e32 v[36:37], 0
	v_mov_b64_e32 v[38:39], 0
	v_mov_b64_e32 v[40:41], 0
	v_mov_b64_e32 v[42:43], 0
	v_mov_b64_e32 v[44:45], 0
	v_mov_b64_e32 v[46:47], 0
	v_mov_b64_e32 v[48:49], 0
	v_mov_b64_e32 v[50:51], 0
	v_mov_b64_e32 v[52:53], 0
	v_mov_b64_e32 v[54:55], 0
	v_mov_b64_e32 v[56:57], 0
	v_mov_b64_e32 v[58:59], 0
	v_mov_b64_e32 v[60:61], 0
	v_mov_b64_e32 v[62:63], 0
	v_mov_b64_e32 v[96:97], 0
	v_mov_b64_e32 v[98:99], 0
	v_mov_b64_e32 v[100:101], 0
	v_mov_b64_e32 v[102:103], 0
	v_mov_b64_e32 v[104:105], 0
	v_mov_b64_e32 v[106:107], 0
	v_mov_b64_e32 v[108:109], 0
	v_mov_b64_e32 v[110:111], 0
	v_mov_b64_e32 v[112:113], 0
	v_mov_b64_e32 v[114:115], 0
	v_mov_b64_e32 v[116:117], 0
	v_mov_b64_e32 v[118:119], 0
	v_mov_b64_e32 v[120:121], 0
	v_mov_b64_e32 v[122:123], 0
	v_mov_b64_e32 v[124:125], 0
	v_mov_b64_e32 v[126:127], 0
	v_mov_b64_e32 v[128:129], 0
	v_mov_b64_e32 v[130:131], 0
	v_mov_b64_e32 v[132:133], 0
	v_mov_b64_e32 v[134:135], 0
	v_mov_b64_e32 v[136:137], 0
	v_mov_b64_e32 v[138:139], 0
	v_mov_b64_e32 v[140:141], 0
	v_mov_b64_e32 v[142:143], 0
	v_mov_b64_e32 v[144:145], 0
	v_mov_b64_e32 v[146:147], 0
	v_mov_b64_e32 v[148:149], 0
	v_mov_b64_e32 v[150:151], 0
	v_mov_b64_e32 v[152:153], 0
	v_mov_b64_e32 v[154:155], 0
	v_mov_b64_e32 v[156:157], 0
	v_mov_b64_e32 v[158:159], 0
	v_lshrrev_b32_e32 v253, 8, v200
	s_nop 0
	v_readfirstlane_b32 s98, v253
	s_cmp_lg_u32 s98, 0
	s_cbranch_scc1 .Lgp_866
	s_setprio 1

.LBB0_1017:
	s_add_u32 s52, s52, 0xb0080
	s_addc_u32 s53, s53, 0
	s_add_u32 s76, s54, 0x100
	s_addc_u32 s77, s55, 0
	s_mov_b32 s78, -2
	v_mov_b64_e32 v[0:1], 0
	v_mov_b64_e32 v[2:3], 0
	v_mov_b64_e32 v[4:5], 0
	v_mov_b64_e32 v[6:7], 0
	v_mov_b64_e32 v[8:9], 0
	v_mov_b64_e32 v[10:11], 0
	v_mov_b64_e32 v[12:13], 0
	v_mov_b64_e32 v[14:15], 0
	v_mov_b64_e32 v[16:17], 0
	v_mov_b64_e32 v[18:19], 0
	v_mov_b64_e32 v[20:21], 0
	v_mov_b64_e32 v[22:23], 0
	v_mov_b64_e32 v[24:25], 0
	v_mov_b64_e32 v[26:27], 0
	v_mov_b64_e32 v[28:29], 0
	v_mov_b64_e32 v[30:31], 0
	v_mov_b64_e32 v[32:33], 0
	v_mov_b64_e32 v[34:35], 0
	v_mov_b64_e32 v[36:37], 0
	v_mov_b64_e32 v[38:39], 0
	v_mov_b64_e32 v[40:41], 0
	v_mov_b64_e32 v[42:43], 0
	v_mov_b64_e32 v[44:45], 0
	v_mov_b64_e32 v[46:47], 0
	v_mov_b64_e32 v[48:49], 0
	v_mov_b64_e32 v[50:51], 0
	v_mov_b64_e32 v[52:53], 0
	v_mov_b64_e32 v[54:55], 0
	v_mov_b64_e32 v[56:57], 0
	v_mov_b64_e32 v[58:59], 0
	v_mov_b64_e32 v[60:61], 0
	v_mov_b64_e32 v[62:63], 0
	v_mov_b64_e32 v[64:65], 0
	v_mov_b64_e32 v[66:67], 0
	v_mov_b64_e32 v[68:69], 0
	v_mov_b64_e32 v[70:71], 0
	v_mov_b64_e32 v[72:73], 0
	v_mov_b64_e32 v[74:75], 0
	v_mov_b64_e32 v[76:77], 0
	v_mov_b64_e32 v[78:79], 0
	v_mov_b64_e32 v[80:81], 0
	v_mov_b64_e32 v[82:83], 0
	v_mov_b64_e32 v[84:85], 0
	v_mov_b64_e32 v[86:87], 0
	v_mov_b64_e32 v[88:89], 0
	v_mov_b64_e32 v[90:91], 0
	v_mov_b64_e32 v[92:93], 0
	v_mov_b64_e32 v[94:95], 0
	v_mov_b64_e32 v[96:97], 0
	v_mov_b64_e32 v[98:99], 0
	v_mov_b64_e32 v[100:101], 0
	v_mov_b64_e32 v[102:103], 0
	v_mov_b64_e32 v[104:105], 0
	v_mov_b64_e32 v[106:107], 0
	v_mov_b64_e32 v[108:109], 0
	v_mov_b64_e32 v[110:111], 0
	v_mov_b64_e32 v[112:113], 0
	v_mov_b64_e32 v[114:115], 0
	v_mov_b64_e32 v[116:117], 0
	v_mov_b64_e32 v[118:119], 0
	v_mov_b64_e32 v[120:121], 0
	v_mov_b64_e32 v[122:123], 0
	v_mov_b64_e32 v[124:125], 0
	v_mov_b64_e32 v[126:127], 0
	v_lshrrev_b32_e32 v253, 8, v200
	s_nop 0
	v_readfirstlane_b32 s98, v253
	s_cmp_lg_u32 s98, 0
	s_cbranch_scc1 .Lgp_1018
	s_setprio 1

.LBB0_1154:
	s_ashr_i32 s15, s14, 31
	s_lshl_b64 s[18:19], s[14:15], 19
	s_add_u32 s18, s17, s18
	s_addc_u32 s19, s52, s19
	s_and_b64 s[20:21], s[2:3], exec
	s_cselect_b32 s15, s19, s35
	s_cselect_b32 s70, s18, s34
	s_ashr_i32 s13, s12, 31
	s_lshl_b64 s[20:21], s[12:13], 19
	s_add_u32 s20, s53, s20
	s_addc_u32 s21, s54, s21
	s_and_b64 s[50:51], s[2:3], exec
	s_cselect_b32 s13, s21, s45
	s_cselect_b32 s71, s20, s44
	s_add_u32 s34, s34, 0x40080
	s_addc_u32 s35, s35, 0
	s_add_u32 s72, s44, 0x100
	s_addc_u32 s73, s45, 0
	s_mov_b32 s74, -2
	v_mov_b64_e32 v[0:1], 0
	v_mov_b64_e32 v[2:3], 0
	v_mov_b64_e32 v[4:5], 0
	v_mov_b64_e32 v[6:7], 0
	v_mov_b64_e32 v[8:9], 0
	v_mov_b64_e32 v[10:11], 0
	v_mov_b64_e32 v[12:13], 0
	v_mov_b64_e32 v[14:15], 0
	v_mov_b64_e32 v[16:17], 0
	v_mov_b64_e32 v[18:19], 0
	v_mov_b64_e32 v[20:21], 0
	v_mov_b64_e32 v[22:23], 0
	v_mov_b64_e32 v[24:25], 0
	v_mov_b64_e32 v[26:27], 0
	v_mov_b64_e32 v[28:29], 0
	v_mov_b64_e32 v[30:31], 0
	v_mov_b64_e32 v[32:33], 0
	v_mov_b64_e32 v[34:35], 0
	v_mov_b64_e32 v[36:37], 0
	v_mov_b64_e32 v[38:39], 0
	v_mov_b64_e32 v[40:41], 0
	v_mov_b64_e32 v[42:43], 0
	v_mov_b64_e32 v[44:45], 0
	v_mov_b64_e32 v[46:47], 0
	v_mov_b64_e32 v[48:49], 0
	v_mov_b64_e32 v[50:51], 0
	v_mov_b64_e32 v[52:53], 0
	v_mov_b64_e32 v[54:55], 0
	v_mov_b64_e32 v[56:57], 0
	v_mov_b64_e32 v[58:59], 0
	v_mov_b64_e32 v[60:61], 0
	v_mov_b64_e32 v[62:63], 0
	v_mov_b64_e32 v[64:65], 0
	v_mov_b64_e32 v[66:67], 0
	v_mov_b64_e32 v[68:69], 0
	v_mov_b64_e32 v[70:71], 0
	v_mov_b64_e32 v[72:73], 0
	v_mov_b64_e32 v[74:75], 0
	v_mov_b64_e32 v[76:77], 0
	v_mov_b64_e32 v[78:79], 0
	v_mov_b64_e32 v[80:81], 0
	v_mov_b64_e32 v[82:83], 0
	v_mov_b64_e32 v[84:85], 0
	v_mov_b64_e32 v[86:87], 0
	v_mov_b64_e32 v[88:89], 0
	v_mov_b64_e32 v[90:91], 0
	v_mov_b64_e32 v[92:93], 0
	v_mov_b64_e32 v[94:95], 0
	v_mov_b64_e32 v[96:97], 0
	v_mov_b64_e32 v[98:99], 0
	v_mov_b64_e32 v[100:101], 0
	v_mov_b64_e32 v[102:103], 0
	v_mov_b64_e32 v[104:105], 0
	v_mov_b64_e32 v[106:107], 0
	v_mov_b64_e32 v[108:109], 0
	v_mov_b64_e32 v[110:111], 0
	v_mov_b64_e32 v[112:113], 0
	v_mov_b64_e32 v[114:115], 0
	v_mov_b64_e32 v[116:117], 0
	v_mov_b64_e32 v[118:119], 0
	v_mov_b64_e32 v[120:121], 0
	v_mov_b64_e32 v[122:123], 0
	v_mov_b64_e32 v[124:125], 0
	v_mov_b64_e32 v[126:127], 0
	v_lshrrev_b32_e32 v253, 8, v200
	s_nop 0
	v_readfirstlane_b32 s98, v253
	s_cmp_lg_u32 s98, 0
	s_cbranch_scc1 .Lgp_1155
	s_setprio 1

.LBB0_1414:
	s_ashr_i32 s51, s50, 31
	s_lshl_b64 s[52:53], s[50:51], 19
	s_add_u32 s52, s13, s52
	s_addc_u32 s53, s17, s53
	s_and_b64 s[54:55], s[2:3], exec
	s_cselect_b32 s51, s53, s57
	s_cselect_b32 s76, s52, s56
	s_ashr_i32 s45, s44, 31
	s_lshl_b64 s[54:55], s[44:45], 19
	s_add_u32 s54, s62, s54
	s_addc_u32 s55, s63, s55
	s_and_b64 s[60:61], s[2:3], exec
	s_cselect_b32 s45, s55, s59
	s_cselect_b32 s77, s54, s58
	s_add_u32 s56, s56, 0x40080
	s_addc_u32 s57, s57, 0
	s_add_u32 s78, s58, 0x100
	s_addc_u32 s79, s59, 0
	s_mov_b32 s80, -2
	v_mov_b64_e32 v[0:1], 0
	v_mov_b64_e32 v[2:3], 0
	v_mov_b64_e32 v[4:5], 0
	v_mov_b64_e32 v[6:7], 0
	v_mov_b64_e32 v[8:9], 0
	v_mov_b64_e32 v[10:11], 0
	v_mov_b64_e32 v[12:13], 0
	v_mov_b64_e32 v[14:15], 0
	v_mov_b64_e32 v[16:17], 0
	v_mov_b64_e32 v[18:19], 0
	v_mov_b64_e32 v[20:21], 0
	v_mov_b64_e32 v[22:23], 0
	v_mov_b64_e32 v[24:25], 0
	v_mov_b64_e32 v[26:27], 0
	v_mov_b64_e32 v[28:29], 0
	v_mov_b64_e32 v[30:31], 0
	v_mov_b64_e32 v[32:33], 0
	v_mov_b64_e32 v[34:35], 0
	v_mov_b64_e32 v[36:37], 0
	v_mov_b64_e32 v[38:39], 0
	v_mov_b64_e32 v[40:41], 0
	v_mov_b64_e32 v[42:43], 0
	v_mov_b64_e32 v[44:45], 0
	v_mov_b64_e32 v[46:47], 0
	v_mov_b64_e32 v[48:49], 0
	v_mov_b64_e32 v[50:51], 0
	v_mov_b64_e32 v[52:53], 0
	v_mov_b64_e32 v[54:55], 0
	v_mov_b64_e32 v[56:57], 0
	v_mov_b64_e32 v[58:59], 0
	v_mov_b64_e32 v[60:61], 0
	v_mov_b64_e32 v[62:63], 0
	v_mov_b64_e32 v[64:65], 0
	v_mov_b64_e32 v[66:67], 0
	v_mov_b64_e32 v[68:69], 0
	v_mov_b64_e32 v[70:71], 0
	v_mov_b64_e32 v[72:73], 0
	v_mov_b64_e32 v[74:75], 0
	v_mov_b64_e32 v[76:77], 0
	v_mov_b64_e32 v[78:79], 0
	v_mov_b64_e32 v[80:81], 0
	v_mov_b64_e32 v[82:83], 0
	v_mov_b64_e32 v[84:85], 0
	v_mov_b64_e32 v[86:87], 0
	v_mov_b64_e32 v[88:89], 0
	v_mov_b64_e32 v[90:91], 0
	v_mov_b64_e32 v[92:93], 0
	v_mov_b64_e32 v[94:95], 0
	v_mov_b64_e32 v[96:97], 0
	v_mov_b64_e32 v[98:99], 0
	v_mov_b64_e32 v[100:101], 0
	v_mov_b64_e32 v[102:103], 0
	v_mov_b64_e32 v[104:105], 0
	v_mov_b64_e32 v[106:107], 0
	v_mov_b64_e32 v[108:109], 0
	v_mov_b64_e32 v[110:111], 0
	v_mov_b64_e32 v[112:113], 0
	v_mov_b64_e32 v[114:115], 0
	v_mov_b64_e32 v[116:117], 0
	v_mov_b64_e32 v[118:119], 0
	v_mov_b64_e32 v[120:121], 0
	v_mov_b64_e32 v[122:123], 0
	v_mov_b64_e32 v[124:125], 0
	v_mov_b64_e32 v[126:127], 0
	s_waitcnt vmcnt(0)
	v_lshrrev_b32_e32 v253, 8, v200
	s_nop 0
	v_readfirstlane_b32 s98, v253
	s_cmp_lg_u32 s98, 0
	s_cbranch_scc1 .Lgp_1415
	s_setprio 1

.LBB0_1551:
	s_ashr_i32 s55, s54, 31
	s_lshl_b64 s[56:57], s[54:55], 19
	s_add_u32 s56, s17, s56
	s_addc_u32 s57, s66, s57
	s_and_b64 s[58:59], s[6:7], exec
	s_cselect_b32 s55, s57, s61
	s_cselect_b32 s84, s56, s60
	s_ashr_i32 s53, s52, 31
	s_lshl_b64 s[58:59], s[52:53], 19
	s_add_u32 s58, s67, s58
	s_addc_u32 s59, s68, s59
	s_and_b64 s[64:65], s[6:7], exec
	s_cselect_b32 s53, s59, s63
	s_cselect_b32 s85, s58, s62
	s_add_u32 s60, s60, 0x40080
	s_addc_u32 s61, s61, 0
	s_add_u32 s86, s62, 0x100
	s_addc_u32 s87, s63, 0
	s_mov_b32 s88, -2
	v_mov_b64_e32 v[0:1], 0
	v_mov_b64_e32 v[2:3], 0
	v_mov_b64_e32 v[4:5], 0
	v_mov_b64_e32 v[6:7], 0
	v_mov_b64_e32 v[8:9], 0
	v_mov_b64_e32 v[10:11], 0
	v_mov_b64_e32 v[12:13], 0
	v_mov_b64_e32 v[14:15], 0
	v_mov_b64_e32 v[16:17], 0
	v_mov_b64_e32 v[18:19], 0
	v_mov_b64_e32 v[20:21], 0
	v_mov_b64_e32 v[22:23], 0
	v_mov_b64_e32 v[24:25], 0
	v_mov_b64_e32 v[26:27], 0
	v_mov_b64_e32 v[28:29], 0
	v_mov_b64_e32 v[30:31], 0
	v_mov_b64_e32 v[32:33], 0
	v_mov_b64_e32 v[34:35], 0
	v_mov_b64_e32 v[36:37], 0
	v_mov_b64_e32 v[38:39], 0
	v_mov_b64_e32 v[40:41], 0
	v_mov_b64_e32 v[42:43], 0
	v_mov_b64_e32 v[44:45], 0
	v_mov_b64_e32 v[46:47], 0
	v_mov_b64_e32 v[48:49], 0
	v_mov_b64_e32 v[50:51], 0
	v_mov_b64_e32 v[52:53], 0
	v_mov_b64_e32 v[54:55], 0
	v_mov_b64_e32 v[56:57], 0
	v_mov_b64_e32 v[58:59], 0
	v_mov_b64_e32 v[60:61], 0
	v_mov_b64_e32 v[62:63], 0
	v_mov_b64_e32 v[96:97], 0
	v_mov_b64_e32 v[98:99], 0
	v_mov_b64_e32 v[100:101], 0
	v_mov_b64_e32 v[102:103], 0
	v_mov_b64_e32 v[104:105], 0
	v_mov_b64_e32 v[106:107], 0
	v_mov_b64_e32 v[108:109], 0
	v_mov_b64_e32 v[110:111], 0
	v_mov_b64_e32 v[112:113], 0
	v_mov_b64_e32 v[114:115], 0
	v_mov_b64_e32 v[116:117], 0
	v_mov_b64_e32 v[118:119], 0
	v_mov_b64_e32 v[120:121], 0
	v_mov_b64_e32 v[122:123], 0
	v_mov_b64_e32 v[124:125], 0
	v_mov_b64_e32 v[126:127], 0
	v_mov_b64_e32 v[128:129], 0
	v_mov_b64_e32 v[130:131], 0
	v_mov_b64_e32 v[132:133], 0
	v_mov_b64_e32 v[134:135], 0
	v_mov_b64_e32 v[136:137], 0
	v_mov_b64_e32 v[138:139], 0
	v_mov_b64_e32 v[140:141], 0
	v_mov_b64_e32 v[142:143], 0
	v_mov_b64_e32 v[144:145], 0
	v_mov_b64_e32 v[146:147], 0
	v_mov_b64_e32 v[148:149], 0
	v_mov_b64_e32 v[150:151], 0
	v_mov_b64_e32 v[152:153], 0
	v_mov_b64_e32 v[154:155], 0
	v_mov_b64_e32 v[156:157], 0
	v_mov_b64_e32 v[158:159], 0
	v_lshrrev_b32_e32 v253, 8, v200
	s_nop 0
	v_readfirstlane_b32 s98, v253
	s_cmp_lg_u32 s98, 0
	s_cbranch_scc1 .Lgp_1552
	s_setprio 1

.LBB0_1703:
	s_add_u32 s44, s44, 0xb0080
	s_addc_u32 s45, s45, 0
	s_add_u32 s66, s46, 0x100
	s_addc_u32 s67, s47, 0
	s_mov_b32 s68, -2
	v_mov_b64_e32 v[0:1], 0
	v_mov_b64_e32 v[2:3], 0
	v_mov_b64_e32 v[4:5], 0
	v_mov_b64_e32 v[6:7], 0
	v_mov_b64_e32 v[8:9], 0
	v_mov_b64_e32 v[10:11], 0
	v_mov_b64_e32 v[12:13], 0
	v_mov_b64_e32 v[14:15], 0
	v_mov_b64_e32 v[16:17], 0
	v_mov_b64_e32 v[18:19], 0
	v_mov_b64_e32 v[20:21], 0
	v_mov_b64_e32 v[22:23], 0
	v_mov_b64_e32 v[24:25], 0
	v_mov_b64_e32 v[26:27], 0
	v_mov_b64_e32 v[28:29], 0
	v_mov_b64_e32 v[30:31], 0
	v_mov_b64_e32 v[32:33], 0
	v_mov_b64_e32 v[34:35], 0
	v_mov_b64_e32 v[36:37], 0
	v_mov_b64_e32 v[38:39], 0
	v_mov_b64_e32 v[40:41], 0
	v_mov_b64_e32 v[42:43], 0
	v_mov_b64_e32 v[44:45], 0
	v_mov_b64_e32 v[46:47], 0
	v_mov_b64_e32 v[48:49], 0
	v_mov_b64_e32 v[50:51], 0
	v_mov_b64_e32 v[52:53], 0
	v_mov_b64_e32 v[54:55], 0
	v_mov_b64_e32 v[56:57], 0
	v_mov_b64_e32 v[58:59], 0
	v_mov_b64_e32 v[60:61], 0
	v_mov_b64_e32 v[62:63], 0
	v_mov_b64_e32 v[64:65], 0
	v_mov_b64_e32 v[66:67], 0
	v_mov_b64_e32 v[68:69], 0
	v_mov_b64_e32 v[70:71], 0
	v_mov_b64_e32 v[72:73], 0
	v_mov_b64_e32 v[74:75], 0
	v_mov_b64_e32 v[76:77], 0
	v_mov_b64_e32 v[78:79], 0
	v_mov_b64_e32 v[80:81], 0
	v_mov_b64_e32 v[82:83], 0
	v_mov_b64_e32 v[84:85], 0
	v_mov_b64_e32 v[86:87], 0
	v_mov_b64_e32 v[88:89], 0
	v_mov_b64_e32 v[90:91], 0
	v_mov_b64_e32 v[92:93], 0
	v_mov_b64_e32 v[94:95], 0
	v_mov_b64_e32 v[96:97], 0
	v_mov_b64_e32 v[98:99], 0
	v_mov_b64_e32 v[100:101], 0
	v_mov_b64_e32 v[102:103], 0
	v_mov_b64_e32 v[104:105], 0
	v_mov_b64_e32 v[106:107], 0
	v_mov_b64_e32 v[108:109], 0
	v_mov_b64_e32 v[110:111], 0
	v_mov_b64_e32 v[112:113], 0
	v_mov_b64_e32 v[114:115], 0
	v_mov_b64_e32 v[116:117], 0
	v_mov_b64_e32 v[118:119], 0
	v_mov_b64_e32 v[120:121], 0
	v_mov_b64_e32 v[122:123], 0
	v_mov_b64_e32 v[124:125], 0
	v_mov_b64_e32 v[126:127], 0
	s_waitcnt vmcnt(0)
	v_lshrrev_b32_e32 v253, 8, v200
	s_nop 0
	v_readfirstlane_b32 s98, v253
	s_cmp_lg_u32 s98, 0
	s_cbranch_scc1 .Lgp_1704
	s_setprio 1
